# NSA select/window attention: extended bias tables for all 8 heads built once per phase instead of per item (two dependent global loads and table writes per item removed)
# baseline (speedup 1.0000x reference)
; template <int MODE>
; __device__ __forceinline__ void attn_pass(LAS unsigned char* lds, const bf16_t* base, int gk, int q0, const float* relb_b, const unsigned* selrow, f32x4 (&o)[2][4]) {
;     ...
;     if (tid < 512) { const int e = tid; lutw[e] = relb_b[(int)T5B[e & 127] * 16 + gk * 4 + (e >> 7)] * LOG2E; }
;     const float bias_far = relb_b[31 * 16 + h] * LOG2E;
.Lattb_tab:
	v_and_b32_e32 v236, 0x7f, v214
	s_getpc_b64 s[10:11]
	s_add_u32 s10, s10, T5B@rel32@lo+4
	s_addc_u32 s11, s11, T5B@rel32@hi+12
	global_load_ubyte v237, v236, s[10:11]
	v_readlane_b32 s52, v255, 8
	v_readlane_b32 s53, v255, 9
	v_ashrrev_i32_e32 v238, 7, v214
	s_waitcnt vmcnt(0)
	v_lshlrev_b32_e32 v237, 4, v237
	v_add_u32_e32 v246, v238, v237
	v_ashrrev_i32_e32 v247, 31, v246
	v_lshl_add_u64 v[246:247], v[246:247], 2, s[52:53]
	global_load_dword v241, v[246:247], off offset:32
	global_load_dword v243, v[246:247], off offset:48
	v_add_u32_e32 v246, 0x1f0, v238
	v_ashrrev_i32_e32 v247, 31, v246
	v_lshl_add_u64 v[246:247], v[246:247], 2, s[52:53]
	global_load_dword v242, v[246:247], off offset:32
	global_load_dword v244, v[246:247], off offset:48
	v_mul_u32_u24_e32 v231, 0xa00, v238
	v_lshl_add_u32 v233, v236, 2, v231
	v_and_b32_e32 v234, 64, v214
	v_lshl_add_u32 v234, v234, 5, v233
	v_mov_b32_e32 v235, 0xf149f2ca
	s_waitcnt vmcnt(0)
	v_mul_f32_e32 v241, 0x3fb8aa3b, v241
	v_mul_f32_e32 v242, 0x3fb8aa3b, v242
	v_mul_f32_e32 v243, 0x3fb8aa3b, v243
	v_mul_f32_e32 v244, 0x3fb8aa3b, v244
	ds_write_b32 v233, v241 offset:41216
	ds_write_b32 v234, v235 offset:40960
	ds_write_b32 v233, v242 offset:41728
	ds_write_b32 v233, v242 offset:42240
	ds_write_b32 v233, v242 offset:42752
	ds_write_b32 v233, v243 offset:51456
	ds_write_b32 v234, v235 offset:51200
	ds_write_b32 v233, v244 offset:51968
	ds_write_b32 v233, v244 offset:52480
	ds_write_b32 v233, v244 offset:52992
	s_waitcnt lgkmcnt(0)
	s_branch .LBB0_49

; template <int MODE>
; __device__ __forceinline__ void attn_pass(LAS unsigned char* lds, const bf16_t* base, int gk, int q0, const float* relb_b, const unsigned* selrow, f32x4 (&o)[2][4]) {
;     ...
;         for (int ks = 0; ks < 2; ++ks) qf[qt][ks] = *(const bf16x8*)(qp + (size_t)(qw0 + qt * 16 + c) * QP + ks * 32 + g * 8);
;     const int kb_hi = q0 >> 6;
;     unsigned todo;
;     unsigned sel[2] = {0xffffffffu, 0xffffffffu};
;     unsigned selw = 0xffffffffu;
;     if (MODE == MODE_BSLC) {
;         sel[0] = selrow[qw0 + c]; sel[1] = selrow[qw0 + 16 + c];
;         unsigned u = sel[0] | sel[1];
; #pragma unroll
;         for (int off = 1; off < 64; off <<= 1) u |= __shfl_xor(u, off);
;         selw = __builtin_amdgcn_readfirstlane(u);
;         unsigned v = selrow[q0 + lane];
; #pragma unroll
;         for (int off = 1; off < 64; off <<= 1) v |= __shfl_xor(v, off);
;         todo = __builtin_amdgcn_readfirstlane(v) & (0xffffffffu >> (31 - kb_hi));
;     } else {
;         const int kb_lo = kb_hi >= 8 ? kb_hi - 8 : 0;
;         todo = (0xffffffffu >> (31 - kb_hi)) & (0xffffffffu << kb_lo);
;     }
;     __syncthreads();
;     if (tid < 512) { const int e = tid; lutw[e] = relb_b[(int)T5B[e & 127] * 16 + gk * 4 + (e >> 7)] * LOG2E; }
;     const float bias_far = relb_b[31 * 16 + h] * LOG2E;
.LBB0_53:
	s_or_b64 exec, exec, s[0:1]
	v_readlane_b32 s0, v254, 48
	s_waitcnt lgkmcnt(0)
	s_barrier
	v_mov_b32_e32 v1, s0
	ds_read_b32 v1, v1
	s_movk_i32 s0, 0x7ff
	s_waitcnt lgkmcnt(0)
	v_cmp_lt_i32_e32 vcc, s0, v1
	v_readfirstlane_b32 s5, v1
	s_mov_b64 s[0:1], -1
	s_cbranch_vccnz .LBB0_48
	s_and_b32 s0, s5, 0xffffffc0
	s_bfe_u32 s19, s5, 0x50001
	s_and_b32 s4, s5, 1
	s_sub_i32 s36, 0x7c0, s0
	s_mul_i32 s0, s19, 0xe18000
	v_readlane_b32 s6, v252, 52
	v_readlane_b32 s7, v252, 53
	s_add_u32 s13, s6, s0
	s_addc_u32 s41, s7, 0
	s_lshl_b32 s40, s4, 2
	s_lshl_b32 s0, s19, 14
	v_readlane_b32 s1, v252, 14
	s_add_u32 s0, s1, s0
	v_readlane_b32 s1, v252, 15
	v_mov_b32_e32 v180, v214
	s_addc_u32 s1, s1, 0
	s_lshl_b32 s5, s4, 13
	v_mov_b32_e32 v10, v214
	s_add_u32 s0, s0, s5
	s_addc_u32 s1, s1, 0
	v_readfirstlane_b32 s5, v10
	s_bfe_u32 s7, s5, 0x20006
	s_or_b32 s8, s7, s40
	s_lshl_b32 s6, s8, 7
	s_add_u32 s10, s13, s6
	s_addc_u32 s11, s41, 0
	s_ashr_i32 s5, s5, 3
	s_and_b32 s6, s5, 0xffffffe0
	v_and_b32_e32 v1, 15, v10
	s_add_i32 s6, s6, s36
	v_or_b32_e32 v2, s6, v1
	v_ashrrev_i32_e32 v3, 31, v2
	v_lshl_add_u64 v[8:9], v[2:3], 2, s[0:1]
	v_and_or_b32 v12, v10, 63, s36
	v_mov_b32_e32 v13, v0
	v_lshl_add_u64 v[12:13], v[12:13], 2, s[0:1]
	global_load_dword v146, v[8:9], off
	global_load_dword v147, v[8:9], off offset:64
	global_load_dword v3, v[12:13], off
	v_mov_b32_e32 v9, v0
	v_and_b32_e32 v8, 48, v10
	v_lshl_add_u64 v[12:13], s[10:11], 0, v[8:9]
	v_or_b32_e32 v9, 16, v2
	v_mad_i64_i32 v[14:15], s[0:1], v2, s85, v[12:13]
	v_mad_i64_i32 v[12:13], s[0:1], v9, s85, v[12:13]
	global_load_dwordx4 v[40:43], v[14:15], off offset:1536
	global_load_dwordx4 v[44:47], v[14:15], off offset:1600
	global_load_dwordx4 v[48:51], v[12:13], off offset:1536
	global_load_dwordx4 v[52:55], v[12:13], off offset:1600
	v_cmp_lt_i32_e32 vcc, v219, v218
	s_barrier
	s_nop 0
	v_cndmask_b32_e32 v9, v217, v219, vcc
	v_lshlrev_b32_e32 v9, 2, v9
	v_cmp_lt_i32_e32 vcc, v220, v218
	s_waitcnt vmcnt(5)
	v_or_b32_e32 v11, v147, v146
	s_waitcnt vmcnt(4)
	ds_bpermute_b32 v12, v9, v3
	ds_bpermute_b32 v9, v9, v11
	v_cndmask_b32_e32 v13, v217, v220, vcc
	v_lshlrev_b32_e32 v13, 2, v13
	v_cmp_lt_i32_e32 vcc, v221, v218
	s_waitcnt lgkmcnt(1)
	v_or_b32_e32 v3, v12, v3
	s_waitcnt lgkmcnt(0)
	v_or_b32_e32 v9, v9, v11
	ds_bpermute_b32 v11, v13, v3
	ds_bpermute_b32 v12, v13, v9
	v_cndmask_b32_e32 v13, v217, v221, vcc
	v_lshlrev_b32_e32 v13, 2, v13
	v_cmp_lt_i32_e32 vcc, v222, v218
	s_waitcnt lgkmcnt(1)
	v_or_b32_e32 v3, v11, v3
	s_waitcnt lgkmcnt(0)
	v_or_b32_e32 v9, v12, v9
	ds_bpermute_b32 v11, v13, v3
	ds_bpermute_b32 v12, v13, v9
	v_cndmask_b32_e32 v13, v217, v222, vcc
	v_lshlrev_b32_e32 v13, 2, v13
	v_cmp_lt_i32_e32 vcc, v223, v218
	s_waitcnt lgkmcnt(1)
	v_or_b32_e32 v3, v11, v3
	s_waitcnt lgkmcnt(0)
	v_or_b32_e32 v9, v12, v9
	ds_bpermute_b32 v11, v13, v3
	ds_bpermute_b32 v12, v13, v9
	v_cndmask_b32_e32 v13, v217, v223, vcc
	v_lshlrev_b32_e32 v178, 2, v13
	v_cmp_lt_i32_e32 vcc, v224, v218
	s_waitcnt lgkmcnt(1)
	v_or_b32_e32 v3, v11, v3
	s_waitcnt lgkmcnt(0)
	v_or_b32_e32 v9, v12, v9
	ds_bpermute_b32 v11, v178, v3
	ds_bpermute_b32 v12, v178, v9
	v_cndmask_b32_e32 v13, v217, v224, vcc
	v_lshlrev_b32_e32 v179, 2, v13
	v_cmp_gt_i32_e32 vcc, s33, v10
	s_waitcnt lgkmcnt(1)
	v_or_b32_e32 v3, v11, v3
	s_waitcnt lgkmcnt(0)
	v_or_b32_e32 v9, v12, v9
	ds_bpermute_b32 v11, v179, v3
	ds_bpermute_b32 v12, v179, v9
	s_waitcnt lgkmcnt(1)
	v_or_b32_e32 v3, v11, v3
	s_waitcnt lgkmcnt(0)
	v_or_b32_e32 v9, v12, v9
	v_readfirstlane_b32 s9, v3
	v_readfirstlane_b32 s44, v9
	s_mov_b64 s[0:1], exec
	s_branch .LBB0_56
	v_and_b32_e32 v3, 0x7f, v10
	s_getpc_b64 s[10:11]
	s_add_u32 s10, s10, T5B@rel32@lo+4
	s_addc_u32 s11, s11, T5B@rel32@hi+12
	global_load_ubyte v3, v3, s[10:11]
	v_ashrrev_i32_e32 v9, 7, v10
	v_readlane_b32 s48, v255, 4
	v_readlane_b32 s52, v255, 8
	v_readlane_b32 s53, v255, 9
	v_readlane_b32 s49, v255, 5
	v_readlane_b32 s50, v255, 6
	v_readlane_b32 s51, v255, 7
	v_readlane_b32 s54, v255, 10
	v_readlane_b32 s55, v255, 11
	v_readlane_b32 s56, v255, 12
	v_readlane_b32 s57, v255, 13
	v_readlane_b32 s58, v255, 14
	v_readlane_b32 s59, v255, 15
	v_readlane_b32 s60, v255, 16
	v_readlane_b32 s61, v255, 17
	v_readlane_b32 s62, v255, 18
	v_readlane_b32 s63, v255, 19
	s_nop 1
	v_add_u32_e32 v228, 0x1f0, v9
	v_add_u32_e32 v228, s40, v228
	v_ashrrev_i32_e32 v229, 31, v228
	v_lshl_add_u64 v[228:229], v[228:229], 2, s[52:53]
	global_load_dword v230, v[228:229], off offset:32
	s_waitcnt vmcnt(0)
	v_lshlrev_b32_e32 v3, 4, v3
	v_add3_u32 v12, v9, s40, v3
	v_ashrrev_i32_e32 v13, 31, v12
	v_lshl_add_u64 v[12:13], v[12:13], 2, s[52:53]
	global_load_dword v3, v[12:13], off offset:32
	v_lshl_add_u32 v9, v10, 2, 0
	s_waitcnt vmcnt(0)
	v_mul_f32_e32 v3, 0x3fb8aa3b, v3
	ds_write_b32 v9, v3 offset:36864
	v_mul_f32_e32 v230, 0x3fb8aa3b, v230
	v_ashrrev_i32_e32 v231, 7, v10
	v_mul_u32_u24_e32 v231, 0xa00, v231
	v_and_b32_e32 v232, 0x7f, v10
	v_lshl_add_u32 v233, v232, 2, v231
	v_and_b32_e32 v234, 64, v10
	v_lshl_add_u32 v234, v234, 5, v233
	v_mov_b32_e32 v235, 0xf149f2ca
	ds_write_b32 v233, v3 offset:41216
	ds_write_b32 v234, v235 offset:40960
	ds_write_b32 v233, v230 offset:41728
	ds_write_b32 v233, v230 offset:42240
	ds_write_b32 v233, v230 offset:42752

; #define LAS __attribute__((address_space(3)))
; #define LDS_BARRIER() asm volatile("s_waitcnt lgkmcnt(0)\n\ts_barrier" ::: "memory")
; template <int MODE>
; __device__ __forceinline__ void attn_pass(LAS unsigned char* lds, const bf16_t* base, int gk, int q0, const float* relb_b, const unsigned* selrow, f32x4 (&o)[2][4]) {
;     ...
;     const float bias_far = relb_b[31 * 16 + h] * LOG2E;
; #pragma unroll
;     for (int qt = 0; qt < 2; ++qt)
; #pragma unroll
;         for (int dt = 0; dt < 4; ++dt) o[qt][dt] = (f32x4){0.f, 0.f, 0.f, 0.f};
;     float mrun[2] = {-1e30f, -1e30f}, lrun[2] = {0.f, 0.f};
;     const int skey = tid >> 3, sch = tid & 7;
;     const unsigned soff = skey * KPB + sch * 16;
;     u32x4 kreg, vreg;
;     int kb = 31 - __builtin_clz(todo); todo &= ~(1u << kb);
;     { const size_t ro = (size_t)(kb * 64 + skey) * QP + sch * 8; kreg = *(const u32x4*)(kp + ro); vreg = *(const u32x4*)(vp + ro); }
;     *(LAS u32x4*)(lds + ATT_KS + soff) = kreg; *(LAS u32x4*)(lds + ATT_VS + soff) = vreg;
;     int kbn = todo ? 31 - __builtin_clz(todo) : -1; if (kbn >= 0) todo &= ~(1u << kbn);
;     if (kbn >= 0) { const size_t ro = (size_t)(kbn * 64 + skey) * QP + sch * 8; kreg = *(const u32x4*)(kp + ro); vreg = *(const u32x4*)(vp + ro); }
;     LDS_BARRIER();
;     int buf = 0;
.LBB0_58:
	v_bfe_u32 v9, v10, 4, 2
	v_mul_f32_e32 v150, 0x3fb8aa3b, v3
	s_and_b64 s[0:1], exec, s[0:1]
	v_lshlrev_b32_e32 v3, 2, v9
	v_lshrrev_b32_e32 v9, 2, v1
	s_cselect_b32 s45, -1, s9
	v_or_b32_e32 v9, v3, v9
	v_lshlrev_b32_e32 v10, 3, v10
	s_lshl_b32 s0, 1, s45
	s_waitcnt lgkmcnt(0)
	s_barrier
	v_mul_u32_u24_e32 v9, 0x90, v9
	v_and_b32_e32 v10, 24, v10
	v_sub_u32_e32 v152, v2, v3
	v_mul_u32_u24_e32 v1, 0x90, v1
	v_mov_b32_e32 v2, v0
	v_mov_b32_e32 v3, v0
	s_andn2_b32 s46, s8, s0
	s_or_b32 s0, s7, s40
	s_lshl_b32 s0, s0, 9
	v_add3_u32 v151, 0, v9, v10
	v_add3_u32 v153, 0, v1, v8
	v_mov_b32_e32 v1, v0
	v_mov_b64_e32 v[22:23], v[2:3]
	v_mov_b64_e32 v[18:19], v[2:3]
	v_mov_b64_e32 v[14:15], v[2:3]
	v_mov_b64_e32 v[10:11], v[2:3]
	v_mov_b64_e32 v[38:39], v[2:3]
	v_mov_b64_e32 v[34:35], v[2:3]
	v_mov_b64_e32 v[26:27], v[2:3]
	v_mov_b64_e32 v[30:31], v[2:3]
	s_add_i32 s47, s0, 0
	s_sub_i32 s48, s6, 63
	s_or_b32 s49, s6, 31
	s_mov_b32 s50, 0
	v_mov_b32_e32 v157, 0xf149f2ca
	v_mov_b32_e32 v154, 0
	v_mov_b64_e32 v[20:21], v[0:1]
	v_mov_b64_e32 v[16:17], v[0:1]
	v_mov_b64_e32 v[12:13], v[0:1]
	v_mov_b64_e32 v[8:9], v[0:1]
	v_mov_b64_e32 v[36:37], v[0:1]
	v_mov_b64_e32 v[32:33], v[0:1]
	v_mov_b64_e32 v[24:25], v[0:1]
	v_mov_b64_e32 v[28:29], v[0:1]
	v_mov_b32_e32 v1, 0
	v_mov_b32_e32 v155, 0xf149f2ca
	s_cmp_lt_i32 s45, 0
	s_cselect_b64 s[6:7], -1, 0
	s_and_b64 vcc, exec, s[6:7]
	s_cbranch_vccnz .LBB0_60

; #define LAS __attribute__((address_space(3)))
; #define LDS_BARRIER() asm volatile("s_waitcnt lgkmcnt(0)\n\ts_barrier" ::: "memory")
; template <int MODE>
; __device__ __forceinline__ void attn_pass(LAS unsigned char* lds, const bf16_t* base, int gk, int q0, const float* relb_b, const unsigned* selrow, f32x4 (&o)[2][4]) {
;     ...
;     const float bias_far = relb_b[31 * 16 + h] * LOG2E;
; #pragma unroll
;     for (int qt = 0; qt < 2; ++qt)
; #pragma unroll
;         for (int dt = 0; dt < 4; ++dt) o[qt][dt] = (f32x4){0.f, 0.f, 0.f, 0.f};
;     float mrun[2] = {-1e30f, -1e30f}, lrun[2] = {0.f, 0.f};
;     const int skey = tid >> 3, sch = tid & 7;
;     const unsigned soff = skey * KPB + sch * 16;
;     u32x4 kreg, vreg;
;     int kb = 31 - __builtin_clz(todo); todo &= ~(1u << kb);
;     { const size_t ro = (size_t)(kb * 64 + skey) * QP + sch * 8; kreg = *(const u32x4*)(kp + ro); vreg = *(const u32x4*)(vp + ro); }
;     *(LAS u32x4*)(lds + ATT_KS + soff) = kreg; *(LAS u32x4*)(lds + ATT_VS + soff) = vreg;
;     int kbn = todo ? 31 - __builtin_clz(todo) : -1; if (kbn >= 0) todo &= ~(1u << kbn);
;     if (kbn >= 0) { const size_t ro = (size_t)(kbn * 64 + skey) * QP + sch * 8; kreg = *(const u32x4*)(kp + ro); vreg = *(const u32x4*)(vp + ro); }
;     LDS_BARRIER();
;     int buf = 0;
.LBB0_147:
	s_waitcnt vmcnt(0)
	v_mul_f32_e32 v188, 0x3fb8aa3b, v1
	v_lshlrev_b32_e32 v189, 2, v42
	v_lshrrev_b32_e32 v1, 2, v40
	v_or_b32_e32 v1, v189, v1
	v_lshlrev_b32_e32 v3, 3, v41
	s_and_b64 s[0:1], exec, s[0:1]
	v_mul_u32_u24_e32 v1, 0x90, v1
	v_and_b32_e32 v3, 24, v3
	s_cselect_b32 s13, -1, s9
	v_add3_u32 v190, 0, v1, v3
	v_mul_u32_u24_e32 v1, 0x90, v40
	s_lshl_b32 s0, 1, s13
	s_waitcnt lgkmcnt(0)
	s_barrier
	v_add3_u32 v194, 0, v1, v2
	v_mov_b32_e32 v2, v0
	v_mov_b32_e32 v3, v0
	s_andn2_b32 s41, s8, s0
	s_or_b32 s0, s7, s40
	s_lshl_b32 s0, s0, 9
	v_mov_b32_e32 v1, v0
	v_mov_b64_e32 v[42:43], v[2:3]
	v_mov_b64_e32 v[46:47], v[2:3]
	v_mov_b64_e32 v[50:51], v[2:3]
	v_mov_b64_e32 v[54:55], v[2:3]
	v_mov_b64_e32 v[58:59], v[2:3]
	v_mov_b64_e32 v[62:63], v[2:3]
	v_mov_b64_e32 v[66:67], v[2:3]
	v_mov_b64_e32 v[70:71], v[2:3]
	s_add_i32 s42, s0, 0
	s_sub_i32 s43, s6, 63
	s_or_b32 s44, s6, 31
	v_or_b32_e32 v191, 1, v189
	v_or_b32_e32 v192, 2, v189
	v_or_b32_e32 v193, 3, v189
	s_mov_b32 s45, 0
	v_mov_b32_e32 v200, 0xf149f2ca
	v_mov_b32_e32 v195, 0
	v_mov_b64_e32 v[40:41], v[0:1]
	v_mov_b64_e32 v[44:45], v[0:1]
	v_mov_b64_e32 v[48:49], v[0:1]
	v_mov_b64_e32 v[52:53], v[0:1]
	v_mov_b64_e32 v[56:57], v[0:1]
	v_mov_b64_e32 v[60:61], v[0:1]
	v_mov_b64_e32 v[64:65], v[0:1]
	v_mov_b64_e32 v[68:69], v[0:1]
	v_mov_b32_e32 v1, 0
	v_mov_b32_e32 v196, 0xf149f2ca
	s_cmp_lt_i32 s13, 0
	s_cselect_b64 s[6:7], -1, 0
	s_and_b64 vcc, exec, s[6:7]
	s_cbranch_vccnz .LBB0_149
